# MLA item epilogue: all eight gate loads issued up front, counted vmcnt(7) waits
# speedup vs baseline: 1.0183x; 1.0183x over previous
; DI u32 pk2(float a, float b) { f2_t v = {a, b}; bf2_t r = __builtin_convertvector(v, bf2_t); return __builtin_bit_cast(u32, r); }
; DI float bflo(u32 u) { return __uint_as_float(u << 16); }
; DI float bfhi(u32 u) { return __uint_as_float(u & 0xffff0000u); }
; DI void pinu(u32& x) { asm volatile("" : "+v"(x)); }
; template <bool DIFF>
; DI void attn_phase(const AttnArgs& a, char* lds) {
;     ...
;     if (!DIFF) {
;       u32 go2 = (u32)qrow * (u32)a.ldg + (u32)(a.goff + h * 128 + 8 * g); pinu(go2);
;       u32 oo2 = (u32)qrow * 2048u + (u32)(h * 128 + 8 * g); pinu(oo2);
; #pragma unroll
;       for (int m = 0; m < NM; ++m)
; #pragma unroll
;         for (int bp = 0; bp < 2; ++bp) {
;           u32x2 pk[2];
;           const u32x4 gl = *(const u32x4*)(a.gate + go2 + 32 * m + 16 * bp);
;           const auto q0 = __builtin_amdgcn_permlane32_swap(gl[0], gl[2], false, false);
;           const auto q1 = __builtin_amdgcn_permlane32_swap(gl[1], gl[3], false, false);
;           u32x2 gsel[2]; gsel[0][0] = q0[0]; gsel[0][1] = q1[0]; gsel[1][0] = q0[1]; gsel[1][1] = q1[1];
; #pragma unroll
;           for (int bb = 0; bb < 2; ++bb) {
;             const int b = 2 * bp + bb;
;             const u32x2 gu = gsel[bb];
;             const float g0 = bflo(gu[0]), g1 = bfhi(gu[0]), g2 = bflo(gu[1]), g3 = bfhi(gu[1]);
;             const float y0 = o[m][4 * b] * inv * g0 * __builtin_amdgcn_rcpf(1.f + __expf(-g0));
;             const float y1 = o[m][4 * b + 1] * inv * g1 * __builtin_amdgcn_rcpf(1.f + __expf(-g1));
;             const float y2 = o[m][4 * b + 2] * inv * g2 * __builtin_amdgcn_rcpf(1.f + __expf(-g2));
;             const float y3 = o[m][4 * b + 3] * inv * g3 * __builtin_amdgcn_rcpf(1.f + __expf(-g3));
;             pk[bb][0] = pk2(y0, y1); pk[bb][1] = pk2(y2, y3);
;           }
;           const auto r0 = __builtin_amdgcn_permlane32_swap(pk[0][0], pk[1][0], false, false);
;           const auto r1 = __builtin_amdgcn_permlane32_swap(pk[0][1], pk[1][1], false, false);
;           u32x4 w; w[0] = r0[0]; w[1] = r1[0]; w[2] = r0[1]; w[3] = r1[1];
;           *(u32x4*)(a.og + oo2 + 32 * m + 16 * bp) = w;
;           __builtin_amdgcn_sched_barrier(0);
;         }
.LBB0_370:
	s_setprio 0
	v_mov_b32_e32 v0, v208
	s_lshl_b32 s0, s62, 7
	v_and_or_b32 v2, v0, 31, s6
	v_lshrrev_b32_e32 v0, 2, v0
	v_mul_lo_u32 v3, v2, s83
	v_and_or_b32 v4, v0, 8, s0
	v_add3_u32 v0, v4, v3, s84
	v_lshl_add_u32 v10, v2, 11, v4
	v_lshl_add_u64 v[2:3], v[0:1], 1, s[42:43]
	global_load_dwordx4 v[84:87], v[2:3], off
	global_load_dwordx4 v[88:91], v[2:3], off offset:32
	global_load_dwordx4 v[92:95], v[2:3], off offset:64
	global_load_dwordx4 v[96:99], v[2:3], off offset:96
	global_load_dwordx4 v[100:103], v[2:3], off offset:128
	global_load_dwordx4 v[104:107], v[2:3], off offset:160
	global_load_dwordx4 v[108:111], v[2:3], off offset:192
	global_load_dwordx4 v[112:115], v[2:3], off offset:224
	v_mov_b32_e32 v0, v217
	s_nop 1
	v_permlane32_swap_b32_e32 v217, v0
	v_add_f32_e32 v0, v217, v0
	v_rcp_f32_e32 v0, v0
	v_mov_b32_e32 v11, v1
	s_add_i32 s33, s33, s34
	v_pk_mul_f32 v[12:13], v[66:67], v[0:1] op_sel_hi:[1,0]
	v_pk_mul_f32 v[14:15], v[68:69], v[0:1] op_sel_hi:[1,0]
	v_pk_mul_f32 v[8:9], v[64:65], v[0:1] op_sel_hi:[1,0]
	v_pk_mul_f32 v[64:65], v[70:71], v[0:1] op_sel_hi:[1,0]
	s_waitcnt vmcnt(7)
	v_mov_b32_e32 v4, v84
	v_mov_b32_e32 v5, v85
	v_mov_b32_e32 v6, v86
	v_mov_b32_e32 v7, v87
	v_mov_b32_e32 v67, v6
	v_mov_b32_e32 v69, v7
	s_nop 0
	v_permlane32_swap_b32_e32 v4, v67
	v_permlane32_swap_b32_e32 v5, v69
	v_lshlrev_b32_e32 v6, 16, v4
	v_and_b32_e32 v7, 0xffff0000, v4
	v_lshlrev_b32_e32 v4, 16, v5
	v_and_b32_e32 v5, 0xffff0000, v5
	v_lshlrev_b32_e32 v66, 16, v67
	v_and_b32_e32 v67, 0xffff0000, v67
	v_lshlrev_b32_e32 v68, 16, v69
	v_and_b32_e32 v69, 0xffff0000, v69
	v_mul_f32_e32 v70, 0xbfb8aa3b, v6
	v_pk_mul_f32 v[8:9], v[8:9], v[6:7]
	v_mul_f32_e32 v71, 0xbfb8aa3b, v7
	v_mul_f32_e32 v80, 0xbfb8aa3b, v4
	v_pk_mul_f32 v[6:7], v[12:13], v[4:5]
	v_mul_f32_e32 v81, 0xbfb8aa3b, v5
	v_mul_f32_e32 v82, 0xbfb8aa3b, v66
	v_pk_mul_f32 v[4:5], v[14:15], v[66:67]
	v_mul_f32_e32 v14, 0xbfb8aa3b, v67
	v_mul_f32_e32 v15, 0xbfb8aa3b, v68
	v_pk_mul_f32 v[12:13], v[64:65], v[68:69]
	v_mul_f32_e32 v64, 0xbfb8aa3b, v69
	v_exp_f32_e32 v65, v70
	v_exp_f32_e32 v66, v71
	v_exp_f32_e32 v67, v80
	v_exp_f32_e32 v68, v81
	v_exp_f32_e32 v69, v82
	v_exp_f32_e32 v14, v14
	v_exp_f32_e32 v15, v15
	v_exp_f32_e32 v64, v64
	v_add_f32_e32 v65, 1.0, v65
	v_add_f32_e32 v66, 1.0, v66
	v_add_f32_e32 v67, 1.0, v67
	v_add_f32_e32 v68, 1.0, v68
	v_add_f32_e32 v69, 1.0, v69
	v_add_f32_e32 v70, 1.0, v14
	v_add_f32_e32 v71, 1.0, v15
	v_add_f32_e32 v80, 1.0, v64
	v_rcp_f32_e32 v14, v65
	v_rcp_f32_e32 v15, v66
	v_rcp_f32_e32 v64, v67
	v_rcp_f32_e32 v65, v68
	v_rcp_f32_e32 v66, v69
	v_rcp_f32_e32 v67, v70
	v_rcp_f32_e32 v68, v71
	v_rcp_f32_e32 v69, v80
	v_pk_mul_f32 v[8:9], v[8:9], v[14:15]
	v_pk_mul_f32 v[14:15], v[6:7], v[64:65]
	v_pk_mul_f32 v[4:5], v[4:5], v[66:67]
	v_pk_mul_f32 v[12:13], v[12:13], v[68:69]
	v_cvt_pk_bf16_f32 v6, v8, v9
	v_cvt_pk_bf16_f32 v7, v14, v15
	v_cvt_pk_bf16_f32 v8, v4, v5
	v_cvt_pk_bf16_f32 v9, v12, v13
	s_nop 0
	v_permlane32_swap_b32_e32 v6, v8
	v_permlane32_swap_b32_e32 v7, v9
	v_lshl_add_u64 v[4:5], v[10:11], 1, s[24:25]
	global_store_dwordx4 v[4:5], v[6:9], off
	v_pk_mul_f32 v[10:11], v[72:73], v[0:1] op_sel_hi:[1,0]
	v_pk_mul_f32 v[12:13], v[74:75], v[0:1] op_sel_hi:[1,0]
	v_pk_mul_f32 v[14:15], v[76:77], v[0:1] op_sel_hi:[1,0]
	v_pk_mul_f32 v[64:65], v[78:79], v[0:1] op_sel_hi:[1,0]
	s_waitcnt vmcnt(7)
	v_mov_b32_e32 v6, v88
	v_mov_b32_e32 v7, v89
	v_mov_b32_e32 v8, v90
	v_mov_b32_e32 v9, v91
	v_mov_b32_e32 v67, v8
	v_mov_b32_e32 v69, v9
	s_nop 0
	v_permlane32_swap_b32_e32 v6, v67
	v_permlane32_swap_b32_e32 v7, v69
	v_lshlrev_b32_e32 v8, 16, v6
	v_and_b32_e32 v9, 0xffff0000, v6
	v_lshlrev_b32_e32 v6, 16, v7
	v_and_b32_e32 v7, 0xffff0000, v7
	v_lshlrev_b32_e32 v66, 16, v67
	v_and_b32_e32 v67, 0xffff0000, v67
	v_lshlrev_b32_e32 v68, 16, v69
	v_and_b32_e32 v69, 0xffff0000, v69
	v_mul_f32_e32 v70, 0xbfb8aa3b, v8
	v_pk_mul_f32 v[10:11], v[10:11], v[8:9]
	v_mul_f32_e32 v71, 0xbfb8aa3b, v9
	v_mul_f32_e32 v72, 0xbfb8aa3b, v6
	v_pk_mul_f32 v[8:9], v[12:13], v[6:7]
	v_mul_f32_e32 v73, 0xbfb8aa3b, v7
	v_mul_f32_e32 v74, 0xbfb8aa3b, v66
	v_pk_mul_f32 v[6:7], v[14:15], v[66:67]
	v_mul_f32_e32 v14, 0xbfb8aa3b, v67
	v_mul_f32_e32 v15, 0xbfb8aa3b, v68
	v_pk_mul_f32 v[12:13], v[64:65], v[68:69]
	v_mul_f32_e32 v64, 0xbfb8aa3b, v69
	v_exp_f32_e32 v65, v70
	v_exp_f32_e32 v66, v71
	v_exp_f32_e32 v67, v72
	v_exp_f32_e32 v68, v73
	v_exp_f32_e32 v69, v74
	v_exp_f32_e32 v14, v14
	v_exp_f32_e32 v15, v15
	v_exp_f32_e32 v64, v64
	v_add_f32_e32 v65, 1.0, v65
	v_add_f32_e32 v66, 1.0, v66
	v_add_f32_e32 v67, 1.0, v67
	v_add_f32_e32 v68, 1.0, v68
	v_add_f32_e32 v69, 1.0, v69
	v_add_f32_e32 v70, 1.0, v14
	v_add_f32_e32 v71, 1.0, v15
	v_add_f32_e32 v72, 1.0, v64
	v_rcp_f32_e32 v14, v65
	v_rcp_f32_e32 v15, v66
	v_rcp_f32_e32 v64, v67
	v_rcp_f32_e32 v65, v68
	v_rcp_f32_e32 v66, v69
	v_rcp_f32_e32 v67, v70
	v_rcp_f32_e32 v68, v71
	v_rcp_f32_e32 v69, v72
	v_pk_mul_f32 v[10:11], v[10:11], v[14:15]
	v_pk_mul_f32 v[8:9], v[8:9], v[64:65]
	v_pk_mul_f32 v[14:15], v[6:7], v[66:67]
	v_pk_mul_f32 v[12:13], v[12:13], v[68:69]
	v_cvt_pk_bf16_f32 v6, v10, v11
	v_cvt_pk_bf16_f32 v7, v8, v9
	v_cvt_pk_bf16_f32 v8, v14, v15
	v_cvt_pk_bf16_f32 v9, v12, v13
	s_nop 0
	v_permlane32_swap_b32_e32 v6, v8
	v_permlane32_swap_b32_e32 v7, v9
	global_store_dwordx4 v[4:5], v[6:9], off offset:32
	v_pk_mul_f32 v[12:13], v[50:51], v[0:1] op_sel_hi:[1,0]
	v_pk_mul_f32 v[14:15], v[52:53], v[0:1] op_sel_hi:[1,0]
	v_pk_mul_f32 v[10:11], v[48:49], v[0:1] op_sel_hi:[1,0]
	v_pk_mul_f32 v[48:49], v[54:55], v[0:1] op_sel_hi:[1,0]
	s_waitcnt vmcnt(7)
; DI u32 pk2(float a, float b) { f2_t v = {a, b}; bf2_t r = __builtin_convertvector(v, bf2_t); return __builtin_bit_cast(u32, r); }
; DI float bflo(u32 u) { return __uint_as_float(u << 16); }
; DI float bfhi(u32 u) { return __uint_as_float(u & 0xffff0000u); }
; template <bool DIFF>
; DI void attn_phase(const AttnArgs& a, char* lds) {
;     ...
; #pragma unroll
;       for (int m = 0; m < NM; ++m)
; #pragma unroll
;         for (int bp = 0; bp < 2; ++bp) {
;           u32x2 pk[2];
;           const u32x4 gl = *(const u32x4*)(a.gate + go2 + 32 * m + 16 * bp);
;           const auto q0 = __builtin_amdgcn_permlane32_swap(gl[0], gl[2], false, false);
;           const auto q1 = __builtin_amdgcn_permlane32_swap(gl[1], gl[3], false, false);
;           u32x2 gsel[2]; gsel[0][0] = q0[0]; gsel[0][1] = q1[0]; gsel[1][0] = q0[1]; gsel[1][1] = q1[1];
; #pragma unroll
;           for (int bb = 0; bb < 2; ++bb) {
;             const int b = 2 * bp + bb;
;             const u32x2 gu = gsel[bb];
;             const float g0 = bflo(gu[0]), g1 = bfhi(gu[0]), g2 = bflo(gu[1]), g3 = bfhi(gu[1]);
;             const float y0 = o[m][4 * b] * inv * g0 * __builtin_amdgcn_rcpf(1.f + __expf(-g0));
;             const float y1 = o[m][4 * b + 1] * inv * g1 * __builtin_amdgcn_rcpf(1.f + __expf(-g1));
;             const float y2 = o[m][4 * b + 2] * inv * g2 * __builtin_amdgcn_rcpf(1.f + __expf(-g2));
;             const float y3 = o[m][4 * b + 3] * inv * g3 * __builtin_amdgcn_rcpf(1.f + __expf(-g3));
;             pk[bb][0] = pk2(y0, y1); pk[bb][1] = pk2(y2, y3);
;           }
;           const auto r0 = __builtin_amdgcn_permlane32_swap(pk[0][0], pk[1][0], false, false);
;           const auto r1 = __builtin_amdgcn_permlane32_swap(pk[0][1], pk[1][1], false, false);
;           u32x4 w; w[0] = r0[0]; w[1] = r1[0]; w[2] = r0[1]; w[3] = r1[1];
;           *(u32x4*)(a.og + oo2 + 32 * m + 16 * bp) = w;
;           __builtin_amdgcn_sched_barrier(0);
;         }
	v_mov_b32_e32 v6, v92
	v_mov_b32_e32 v7, v93
	v_mov_b32_e32 v8, v94
	v_mov_b32_e32 v9, v95
	v_mov_b32_e32 v51, v8
	v_mov_b32_e32 v53, v9
	s_nop 0
	v_permlane32_swap_b32_e32 v6, v51
	v_permlane32_swap_b32_e32 v7, v53
	v_lshlrev_b32_e32 v8, 16, v6
	v_and_b32_e32 v9, 0xffff0000, v6
	v_lshlrev_b32_e32 v6, 16, v7
	v_and_b32_e32 v7, 0xffff0000, v7
	v_lshlrev_b32_e32 v50, 16, v51
	v_and_b32_e32 v51, 0xffff0000, v51
	v_lshlrev_b32_e32 v52, 16, v53
	v_and_b32_e32 v53, 0xffff0000, v53
	v_mul_f32_e32 v54, 0xbfb8aa3b, v8
	v_pk_mul_f32 v[10:11], v[10:11], v[8:9]
	v_mul_f32_e32 v55, 0xbfb8aa3b, v9
	v_mul_f32_e32 v64, 0xbfb8aa3b, v6
	v_pk_mul_f32 v[8:9], v[12:13], v[6:7]
	v_mul_f32_e32 v65, 0xbfb8aa3b, v7
	v_mul_f32_e32 v66, 0xbfb8aa3b, v50
	v_pk_mul_f32 v[6:7], v[14:15], v[50:51]
	v_mul_f32_e32 v14, 0xbfb8aa3b, v51
	v_mul_f32_e32 v15, 0xbfb8aa3b, v52
	v_pk_mul_f32 v[12:13], v[48:49], v[52:53]
	v_mul_f32_e32 v48, 0xbfb8aa3b, v53
	v_exp_f32_e32 v49, v54
	v_exp_f32_e32 v50, v55
	v_exp_f32_e32 v51, v64
	v_exp_f32_e32 v52, v65
	v_exp_f32_e32 v53, v66
	v_exp_f32_e32 v14, v14
	v_exp_f32_e32 v15, v15
	v_exp_f32_e32 v48, v48
	v_add_f32_e32 v49, 1.0, v49
	v_add_f32_e32 v50, 1.0, v50
	v_add_f32_e32 v51, 1.0, v51
	v_add_f32_e32 v52, 1.0, v52
	v_add_f32_e32 v53, 1.0, v53
	v_add_f32_e32 v54, 1.0, v14
	v_add_f32_e32 v55, 1.0, v15
	v_add_f32_e32 v64, 1.0, v48
	v_rcp_f32_e32 v14, v49
	v_rcp_f32_e32 v15, v50
	v_rcp_f32_e32 v48, v51
	v_rcp_f32_e32 v49, v52
	v_rcp_f32_e32 v50, v53
	v_rcp_f32_e32 v51, v54
	v_rcp_f32_e32 v52, v55
	v_rcp_f32_e32 v53, v64
	v_pk_mul_f32 v[10:11], v[10:11], v[14:15]
	v_pk_mul_f32 v[8:9], v[8:9], v[48:49]
	v_pk_mul_f32 v[14:15], v[6:7], v[50:51]
	v_pk_mul_f32 v[12:13], v[12:13], v[52:53]
	v_cvt_pk_bf16_f32 v6, v10, v11
	v_cvt_pk_bf16_f32 v7, v8, v9
	v_cvt_pk_bf16_f32 v8, v14, v15
	v_cvt_pk_bf16_f32 v9, v12, v13
	s_nop 0
	v_permlane32_swap_b32_e32 v6, v8
	v_permlane32_swap_b32_e32 v7, v9
	global_store_dwordx4 v[4:5], v[6:9], off offset:64
	v_pk_mul_f32 v[10:11], v[56:57], v[0:1] op_sel_hi:[1,0]
	v_pk_mul_f32 v[12:13], v[58:59], v[0:1] op_sel_hi:[1,0]
	v_pk_mul_f32 v[14:15], v[60:61], v[0:1] op_sel_hi:[1,0]
	v_pk_mul_f32 v[48:49], v[62:63], v[0:1] op_sel_hi:[1,0]
	s_waitcnt vmcnt(7)
	v_mov_b32_e32 v6, v96
	v_mov_b32_e32 v7, v97
	v_mov_b32_e32 v8, v98
	v_mov_b32_e32 v9, v99
	v_mov_b32_e32 v51, v8
	v_mov_b32_e32 v53, v9
	s_nop 0
	v_permlane32_swap_b32_e32 v6, v51
	v_permlane32_swap_b32_e32 v7, v53
	v_lshlrev_b32_e32 v8, 16, v6
	v_and_b32_e32 v9, 0xffff0000, v6
	v_lshlrev_b32_e32 v6, 16, v7
	v_and_b32_e32 v7, 0xffff0000, v7
	v_lshlrev_b32_e32 v50, 16, v51
	v_and_b32_e32 v51, 0xffff0000, v51
	v_lshlrev_b32_e32 v52, 16, v53
	v_and_b32_e32 v53, 0xffff0000, v53
	v_mul_f32_e32 v54, 0xbfb8aa3b, v8
	v_pk_mul_f32 v[10:11], v[10:11], v[8:9]
	v_mul_f32_e32 v55, 0xbfb8aa3b, v9
	v_mul_f32_e32 v56, 0xbfb8aa3b, v6
	v_pk_mul_f32 v[8:9], v[12:13], v[6:7]
	v_mul_f32_e32 v57, 0xbfb8aa3b, v7
	v_mul_f32_e32 v58, 0xbfb8aa3b, v50
	v_pk_mul_f32 v[6:7], v[14:15], v[50:51]
	v_mul_f32_e32 v14, 0xbfb8aa3b, v51
	v_mul_f32_e32 v15, 0xbfb8aa3b, v52
	v_pk_mul_f32 v[12:13], v[48:49], v[52:53]
	v_mul_f32_e32 v48, 0xbfb8aa3b, v53
	v_exp_f32_e32 v49, v54
	v_exp_f32_e32 v50, v55
	v_exp_f32_e32 v51, v56
	v_exp_f32_e32 v52, v57
	v_exp_f32_e32 v53, v58
	v_exp_f32_e32 v14, v14
	v_exp_f32_e32 v15, v15
	v_exp_f32_e32 v48, v48
	v_add_f32_e32 v49, 1.0, v49
	v_add_f32_e32 v50, 1.0, v50
	v_add_f32_e32 v51, 1.0, v51
	v_add_f32_e32 v52, 1.0, v52
	v_add_f32_e32 v53, 1.0, v53
	v_add_f32_e32 v54, 1.0, v14
	v_add_f32_e32 v55, 1.0, v15
	v_add_f32_e32 v56, 1.0, v48
	v_rcp_f32_e32 v14, v49
	v_rcp_f32_e32 v15, v50
	v_rcp_f32_e32 v48, v51
	v_rcp_f32_e32 v49, v52
	v_rcp_f32_e32 v50, v53
	v_rcp_f32_e32 v51, v54
	v_rcp_f32_e32 v52, v55
	v_rcp_f32_e32 v53, v56
	v_pk_mul_f32 v[10:11], v[10:11], v[14:15]
	v_pk_mul_f32 v[8:9], v[8:9], v[48:49]
	v_pk_mul_f32 v[14:15], v[6:7], v[50:51]
	v_pk_mul_f32 v[12:13], v[12:13], v[52:53]
	v_cvt_pk_bf16_f32 v6, v10, v11
	v_cvt_pk_bf16_f32 v7, v8, v9
	v_cvt_pk_bf16_f32 v8, v14, v15
	v_cvt_pk_bf16_f32 v9, v12, v13
	s_nop 0
	v_permlane32_swap_b32_e32 v6, v8
	v_permlane32_swap_b32_e32 v7, v9
	global_store_dwordx4 v[4:5], v[6:9], off offset:96
	v_pk_mul_f32 v[12:13], v[34:35], v[0:1] op_sel_hi:[1,0]
	v_pk_mul_f32 v[14:15], v[36:37], v[0:1] op_sel_hi:[1,0]
	v_pk_mul_f32 v[10:11], v[32:33], v[0:1] op_sel_hi:[1,0]
	v_pk_mul_f32 v[32:33], v[38:39], v[0:1] op_sel_hi:[1,0]
	s_waitcnt vmcnt(7)
	v_mov_b32_e32 v6, v100
	v_mov_b32_e32 v7, v101
	v_mov_b32_e32 v8, v102
	v_mov_b32_e32 v9, v103
	v_mov_b32_e32 v35, v8
	v_mov_b32_e32 v37, v9
	s_nop 0
	v_permlane32_swap_b32_e32 v6, v35
	v_permlane32_swap_b32_e32 v7, v37
	v_lshlrev_b32_e32 v8, 16, v6
	v_and_b32_e32 v9, 0xffff0000, v6
	v_lshlrev_b32_e32 v6, 16, v7
	v_and_b32_e32 v7, 0xffff0000, v7
	v_lshlrev_b32_e32 v34, 16, v35
	v_and_b32_e32 v35, 0xffff0000, v35
	v_lshlrev_b32_e32 v36, 16, v37
	v_and_b32_e32 v37, 0xffff0000, v37
	v_mul_f32_e32 v38, 0xbfb8aa3b, v8
	v_pk_mul_f32 v[10:11], v[10:11], v[8:9]
	v_mul_f32_e32 v39, 0xbfb8aa3b, v9
	v_mul_f32_e32 v48, 0xbfb8aa3b, v6
	v_pk_mul_f32 v[8:9], v[12:13], v[6:7]
	v_mul_f32_e32 v49, 0xbfb8aa3b, v7
	v_mul_f32_e32 v50, 0xbfb8aa3b, v34
	v_pk_mul_f32 v[6:7], v[14:15], v[34:35]
	v_mul_f32_e32 v14, 0xbfb8aa3b, v35
	v_mul_f32_e32 v15, 0xbfb8aa3b, v36
	v_pk_mul_f32 v[12:13], v[32:33], v[36:37]
	v_mul_f32_e32 v32, 0xbfb8aa3b, v37
	v_exp_f32_e32 v33, v38
	v_exp_f32_e32 v34, v39
	v_exp_f32_e32 v35, v48
	v_exp_f32_e32 v36, v49
	v_exp_f32_e32 v37, v50
	v_exp_f32_e32 v14, v14
	v_exp_f32_e32 v15, v15
	v_exp_f32_e32 v32, v32
	v_add_f32_e32 v33, 1.0, v33
	v_add_f32_e32 v34, 1.0, v34
	v_add_f32_e32 v35, 1.0, v35
	v_add_f32_e32 v36, 1.0, v36
	v_add_f32_e32 v37, 1.0, v37
	v_add_f32_e32 v38, 1.0, v14
	v_add_f32_e32 v39, 1.0, v15
	v_add_f32_e32 v48, 1.0, v32
	v_rcp_f32_e32 v14, v33
	v_rcp_f32_e32 v15, v34
	v_rcp_f32_e32 v32, v35
	v_rcp_f32_e32 v33, v36
	v_rcp_f32_e32 v34, v37
	v_rcp_f32_e32 v35, v38
	v_rcp_f32_e32 v36, v39
	v_rcp_f32_e32 v37, v48
	v_pk_mul_f32 v[10:11], v[10:11], v[14:15]
	v_pk_mul_f32 v[8:9], v[8:9], v[32:33]
	v_pk_mul_f32 v[14:15], v[6:7], v[34:35]
	v_pk_mul_f32 v[12:13], v[12:13], v[36:37]
	v_cvt_pk_bf16_f32 v6, v10, v11
	v_cvt_pk_bf16_f32 v7, v8, v9
	v_cvt_pk_bf16_f32 v8, v14, v15
	v_cvt_pk_bf16_f32 v9, v12, v13
	s_nop 0
	v_permlane32_swap_b32_e32 v6, v8
	v_permlane32_swap_b32_e32 v7, v9
	global_store_dwordx4 v[4:5], v[6:9], off offset:128
	v_pk_mul_f32 v[10:11], v[40:41], v[0:1] op_sel_hi:[1,0]
	v_pk_mul_f32 v[12:13], v[42:43], v[0:1] op_sel_hi:[1,0]
	v_pk_mul_f32 v[14:15], v[44:45], v[0:1] op_sel_hi:[1,0]
	v_pk_mul_f32 v[32:33], v[46:47], v[0:1] op_sel_hi:[1,0]
	s_waitcnt vmcnt(7)
; DI u32 pk2(float a, float b) { f2_t v = {a, b}; bf2_t r = __builtin_convertvector(v, bf2_t); return __builtin_bit_cast(u32, r); }
; DI float bflo(u32 u) { return __uint_as_float(u << 16); }
; DI float bfhi(u32 u) { return __uint_as_float(u & 0xffff0000u); }
; template <bool DIFF>
; DI void attn_phase(const AttnArgs& a, char* lds) {
;     ...
; #pragma unroll
;       for (int m = 0; m < NM; ++m)
; #pragma unroll
;         for (int bp = 0; bp < 2; ++bp) {
;           u32x2 pk[2];
;           const u32x4 gl = *(const u32x4*)(a.gate + go2 + 32 * m + 16 * bp);
;           const auto q0 = __builtin_amdgcn_permlane32_swap(gl[0], gl[2], false, false);
;           const auto q1 = __builtin_amdgcn_permlane32_swap(gl[1], gl[3], false, false);
;           u32x2 gsel[2]; gsel[0][0] = q0[0]; gsel[0][1] = q1[0]; gsel[1][0] = q0[1]; gsel[1][1] = q1[1];
; #pragma unroll
;           for (int bb = 0; bb < 2; ++bb) {
;             const int b = 2 * bp + bb;
;             const u32x2 gu = gsel[bb];
;             const float g0 = bflo(gu[0]), g1 = bfhi(gu[0]), g2 = bflo(gu[1]), g3 = bfhi(gu[1]);
;             const float y0 = o[m][4 * b] * inv * g0 * __builtin_amdgcn_rcpf(1.f + __expf(-g0));
;             const float y1 = o[m][4 * b + 1] * inv * g1 * __builtin_amdgcn_rcpf(1.f + __expf(-g1));
;             const float y2 = o[m][4 * b + 2] * inv * g2 * __builtin_amdgcn_rcpf(1.f + __expf(-g2));
;             const float y3 = o[m][4 * b + 3] * inv * g3 * __builtin_amdgcn_rcpf(1.f + __expf(-g3));
;             pk[bb][0] = pk2(y0, y1); pk[bb][1] = pk2(y2, y3);
;           }
;           const auto r0 = __builtin_amdgcn_permlane32_swap(pk[0][0], pk[1][0], false, false);
;           const auto r1 = __builtin_amdgcn_permlane32_swap(pk[0][1], pk[1][1], false, false);
;           u32x4 w; w[0] = r0[0]; w[1] = r1[0]; w[2] = r0[1]; w[3] = r1[1];
;           *(u32x4*)(a.og + oo2 + 32 * m + 16 * bp) = w;
;           __builtin_amdgcn_sched_barrier(0);
;         }
	v_mov_b32_e32 v6, v104
	v_mov_b32_e32 v7, v105
	v_mov_b32_e32 v8, v106
	v_mov_b32_e32 v9, v107
	v_mov_b32_e32 v35, v8
	v_mov_b32_e32 v37, v9
	s_nop 0
	v_permlane32_swap_b32_e32 v6, v35
	v_permlane32_swap_b32_e32 v7, v37
	v_lshlrev_b32_e32 v8, 16, v6
	v_and_b32_e32 v9, 0xffff0000, v6
	v_lshlrev_b32_e32 v6, 16, v7
	v_and_b32_e32 v7, 0xffff0000, v7
	v_lshlrev_b32_e32 v34, 16, v35
	v_and_b32_e32 v35, 0xffff0000, v35
	v_lshlrev_b32_e32 v36, 16, v37
	v_and_b32_e32 v37, 0xffff0000, v37
	v_mul_f32_e32 v38, 0xbfb8aa3b, v8
	v_pk_mul_f32 v[10:11], v[10:11], v[8:9]
	v_mul_f32_e32 v39, 0xbfb8aa3b, v9
	v_mul_f32_e32 v40, 0xbfb8aa3b, v6
	v_pk_mul_f32 v[8:9], v[12:13], v[6:7]
	v_mul_f32_e32 v41, 0xbfb8aa3b, v7
	v_mul_f32_e32 v42, 0xbfb8aa3b, v34
	v_pk_mul_f32 v[6:7], v[14:15], v[34:35]
	v_mul_f32_e32 v14, 0xbfb8aa3b, v35
	v_mul_f32_e32 v15, 0xbfb8aa3b, v36
	v_pk_mul_f32 v[12:13], v[32:33], v[36:37]
	v_mul_f32_e32 v32, 0xbfb8aa3b, v37
	v_exp_f32_e32 v33, v38
	v_exp_f32_e32 v34, v39
	v_exp_f32_e32 v35, v40
	v_exp_f32_e32 v36, v41
	v_exp_f32_e32 v37, v42
	v_exp_f32_e32 v14, v14
	v_exp_f32_e32 v15, v15
	v_exp_f32_e32 v32, v32
	v_add_f32_e32 v33, 1.0, v33
	v_add_f32_e32 v34, 1.0, v34
	v_add_f32_e32 v35, 1.0, v35
	v_add_f32_e32 v36, 1.0, v36
	v_add_f32_e32 v37, 1.0, v37
	v_add_f32_e32 v38, 1.0, v14
	v_add_f32_e32 v39, 1.0, v15
	v_add_f32_e32 v40, 1.0, v32
	v_rcp_f32_e32 v14, v33
	v_rcp_f32_e32 v15, v34
	v_rcp_f32_e32 v32, v35
	v_rcp_f32_e32 v33, v36
	v_rcp_f32_e32 v34, v37
	v_rcp_f32_e32 v35, v38
	v_rcp_f32_e32 v36, v39
	v_rcp_f32_e32 v37, v40
	v_pk_mul_f32 v[10:11], v[10:11], v[14:15]
	v_pk_mul_f32 v[8:9], v[8:9], v[32:33]
	v_pk_mul_f32 v[14:15], v[6:7], v[34:35]
	v_pk_mul_f32 v[12:13], v[12:13], v[36:37]
	v_cvt_pk_bf16_f32 v6, v10, v11
	v_cvt_pk_bf16_f32 v7, v8, v9
	v_cvt_pk_bf16_f32 v8, v14, v15
	v_cvt_pk_bf16_f32 v9, v12, v13
	s_nop 0
	v_permlane32_swap_b32_e32 v6, v8
	v_permlane32_swap_b32_e32 v7, v9
	global_store_dwordx4 v[4:5], v[6:9], off offset:160
	v_pk_mul_f32 v[12:13], v[18:19], v[0:1] op_sel_hi:[1,0]
	v_pk_mul_f32 v[14:15], v[20:21], v[0:1] op_sel_hi:[1,0]
	v_pk_mul_f32 v[10:11], v[16:17], v[0:1] op_sel_hi:[1,0]
	v_pk_mul_f32 v[16:17], v[22:23], v[0:1] op_sel_hi:[1,0]
	s_waitcnt vmcnt(7)
	v_mov_b32_e32 v6, v108
	v_mov_b32_e32 v7, v109
	v_mov_b32_e32 v8, v110
	v_mov_b32_e32 v9, v111
	v_mov_b32_e32 v19, v8
	v_mov_b32_e32 v21, v9
	s_nop 0
	v_permlane32_swap_b32_e32 v6, v19
	v_permlane32_swap_b32_e32 v7, v21
	v_lshlrev_b32_e32 v8, 16, v6
	v_and_b32_e32 v9, 0xffff0000, v6
	v_lshlrev_b32_e32 v6, 16, v7
	v_and_b32_e32 v7, 0xffff0000, v7
	v_lshlrev_b32_e32 v18, 16, v19
	v_and_b32_e32 v19, 0xffff0000, v19
	v_lshlrev_b32_e32 v20, 16, v21
	v_and_b32_e32 v21, 0xffff0000, v21
	v_mul_f32_e32 v22, 0xbfb8aa3b, v8
	v_pk_mul_f32 v[10:11], v[10:11], v[8:9]
	v_mul_f32_e32 v23, 0xbfb8aa3b, v9
	v_mul_f32_e32 v32, 0xbfb8aa3b, v6
	v_pk_mul_f32 v[8:9], v[12:13], v[6:7]
	v_mul_f32_e32 v33, 0xbfb8aa3b, v7
	v_mul_f32_e32 v34, 0xbfb8aa3b, v18
	v_pk_mul_f32 v[6:7], v[14:15], v[18:19]
	v_mul_f32_e32 v14, 0xbfb8aa3b, v19
	v_mul_f32_e32 v15, 0xbfb8aa3b, v20
	v_pk_mul_f32 v[12:13], v[16:17], v[20:21]
	v_mul_f32_e32 v16, 0xbfb8aa3b, v21
	v_exp_f32_e32 v17, v22
	v_exp_f32_e32 v18, v23
	v_exp_f32_e32 v19, v32
	v_exp_f32_e32 v20, v33
	v_exp_f32_e32 v21, v34
	v_exp_f32_e32 v14, v14
	v_exp_f32_e32 v15, v15
	v_exp_f32_e32 v16, v16
	v_add_f32_e32 v17, 1.0, v17
	v_add_f32_e32 v18, 1.0, v18
	v_add_f32_e32 v19, 1.0, v19
	v_add_f32_e32 v20, 1.0, v20
	v_add_f32_e32 v21, 1.0, v21
	v_add_f32_e32 v22, 1.0, v14
	v_add_f32_e32 v23, 1.0, v15
	v_add_f32_e32 v32, 1.0, v16
	v_rcp_f32_e32 v14, v17
	v_rcp_f32_e32 v15, v18
	v_rcp_f32_e32 v16, v19
	v_rcp_f32_e32 v17, v20
	v_rcp_f32_e32 v18, v21
	v_rcp_f32_e32 v19, v22
	v_rcp_f32_e32 v20, v23
	v_rcp_f32_e32 v21, v32
	v_pk_mul_f32 v[10:11], v[10:11], v[14:15]
	v_pk_mul_f32 v[8:9], v[8:9], v[16:17]
	v_pk_mul_f32 v[14:15], v[6:7], v[18:19]
	v_pk_mul_f32 v[12:13], v[12:13], v[20:21]
	v_cvt_pk_bf16_f32 v6, v10, v11
	v_cvt_pk_bf16_f32 v7, v8, v9
	v_cvt_pk_bf16_f32 v8, v14, v15
	v_cvt_pk_bf16_f32 v9, v12, v13
	s_nop 0
	v_permlane32_swap_b32_e32 v6, v8
	v_permlane32_swap_b32_e32 v7, v9
	global_store_dwordx4 v[4:5], v[6:9], off offset:192
	v_pk_mul_f32 v[2:3], v[24:25], v[0:1] op_sel_hi:[1,0]
	v_pk_mul_f32 v[10:11], v[26:27], v[0:1] op_sel_hi:[1,0]
	v_pk_mul_f32 v[12:13], v[28:29], v[0:1] op_sel_hi:[1,0]
	v_pk_mul_f32 v[14:15], v[30:31], v[0:1] op_sel_hi:[1,0]
	s_waitcnt vmcnt(7)
	v_mov_b32_e32 v6, v112
	v_mov_b32_e32 v7, v113
	v_mov_b32_e32 v8, v114
	v_mov_b32_e32 v9, v115
	v_mov_b32_e32 v0, v8
	v_mov_b32_e32 v19, v9
	s_nop 0
	v_permlane32_swap_b32_e32 v6, v0
	v_permlane32_swap_b32_e32 v7, v19
	v_lshlrev_b32_e32 v8, 16, v6
	v_and_b32_e32 v9, 0xffff0000, v6
	v_lshlrev_b32_e32 v6, 16, v7
	v_and_b32_e32 v7, 0xffff0000, v7
	v_lshlrev_b32_e32 v16, 16, v0
	v_and_b32_e32 v17, 0xffff0000, v0
	v_lshlrev_b32_e32 v18, 16, v19
	v_and_b32_e32 v19, 0xffff0000, v19
	v_mul_f32_e32 v0, 0xbfb8aa3b, v8
	v_pk_mul_f32 v[2:3], v[2:3], v[8:9]
	v_mul_f32_e32 v20, 0xbfb8aa3b, v9
	v_mul_f32_e32 v21, 0xbfb8aa3b, v6
	v_pk_mul_f32 v[8:9], v[10:11], v[6:7]
	v_mul_f32_e32 v22, 0xbfb8aa3b, v7
	v_mul_f32_e32 v23, 0xbfb8aa3b, v16
	v_pk_mul_f32 v[6:7], v[12:13], v[16:17]
	v_mul_f32_e32 v12, 0xbfb8aa3b, v17
	v_mul_f32_e32 v13, 0xbfb8aa3b, v18
	v_pk_mul_f32 v[10:11], v[14:15], v[18:19]
	v_mul_f32_e32 v14, 0xbfb8aa3b, v19
	v_exp_f32_e32 v0, v0
	v_exp_f32_e32 v15, v20
	v_exp_f32_e32 v16, v21
	v_exp_f32_e32 v17, v22
	v_exp_f32_e32 v18, v23
	v_exp_f32_e32 v12, v12
	v_exp_f32_e32 v13, v13
	v_exp_f32_e32 v14, v14
	v_add_f32_e32 v0, 1.0, v0
	v_add_f32_e32 v15, 1.0, v15
	v_add_f32_e32 v16, 1.0, v16
	v_add_f32_e32 v17, 1.0, v17
	v_add_f32_e32 v18, 1.0, v18
	v_add_f32_e32 v19, 1.0, v12
	v_add_f32_e32 v20, 1.0, v13
	v_add_f32_e32 v21, 1.0, v14
	v_rcp_f32_e32 v12, v0
	v_rcp_f32_e32 v13, v15
	v_rcp_f32_e32 v14, v16
	v_rcp_f32_e32 v15, v17
	v_rcp_f32_e32 v16, v18
	v_rcp_f32_e32 v17, v19
	v_rcp_f32_e32 v18, v20
	v_rcp_f32_e32 v19, v21
	v_pk_mul_f32 v[2:3], v[2:3], v[12:13]
	v_pk_mul_f32 v[8:9], v[8:9], v[14:15]
	v_pk_mul_f32 v[12:13], v[6:7], v[16:17]
	v_pk_mul_f32 v[10:11], v[10:11], v[18:19]
	v_cvt_pk_bf16_f32 v6, v2, v3
	v_cvt_pk_bf16_f32 v7, v8, v9
	v_cvt_pk_bf16_f32 v8, v12, v13
	v_cvt_pk_bf16_f32 v9, v10, v11
	s_nop 0
	v_permlane32_swap_b32_e32 v6, v8
	v_permlane32_swap_b32_e32 v7, v9
	global_store_dwordx4 v[4:5], v[6:9], off offset:224
	s_cmpk_gt_i32 s33, 0x3ff
	s_cbranch_scc1 .LBB0_407
